# no per-phase setprio flips; one static s_setprio 1 for waves 4-7 at kernel entry
# baseline (speedup 1.0000x reference)
; #define LAS __attribute__((address_space(3)))
; __device__ __forceinline__ unsigned xb_add(unsigned* p, unsigned v) { return __hip_atomic_fetch_add(p, v, __ATOMIC_RELAXED, __HIP_MEMORY_SCOPE_AGENT); }
; __device__ __forceinline__ unsigned xb_xcc_id() { return (unsigned)__builtin_amdgcn_s_getreg((3 << 11) | 20) & 0xFu; }
; __device__ __forceinline__ XcdBarrier xcd_barrier_post(unsigned* bar, volatile LAS unsigned* st) {
;     XcdBarrier b; b.bar = bar; b.x = xb_xcc_id(); b.st = st;
;     if (threadIdx.x == 0) (void)xb_add(&bar[XB_XCNT(b.x)], 1u);
;     return b;
; }
; __global__ void __launch_bounds__(512, 2) hybrid_fwd(Params p) {
;     extern __shared__ __attribute__((aligned(16))) unsigned char shm[];
;     LAS unsigned char* lds = (LAS unsigned char*)shm;
;     cg::grid_group grid = cg::this_grid();
;     const int tid = threadIdx.x, G = gridDim.x;
;     unsigned char* ws = p.ws;
;     volatile LAS unsigned* ctlw = (volatile LAS unsigned*)(lds + 131072);
;     if (tid < 64) ctlw[tid] = 0u;
;     __syncthreads();
;     const XcdBarrier xbar = xcd_barrier_post((unsigned*)(ws + WS_BAR), ctlw + 8);
_Z10hybrid_fwd6Params:
	v_readfirstlane_b32 s98, v0
	s_nop 0
	s_and_b32 s98, s98, 0x3ff
	s_lshr_b32 s98, s98, 6
	s_cmp_ge_u32 s98, 4
	s_cbranch_scc0 .Lprio_done
	s_setprio 1
.Lprio_done:
	s_load_dwordx8 s[4:11], s[0:1], 0x40
	s_load_dword s33, s[0:1], 0x78
	s_load_dwordx4 s[64:67], s[0:1], 0x60
	s_load_dwordx2 s[28:29], s[0:1], 0x70
	s_add_u32 s16, s0, 0x70
	v_and_b32_e32 v180, 0x3ff, v0
	s_addc_u32 s17, s1, 0
	s_waitcnt lgkmcnt(0)
	v_writelane_b32 v252, s4, 0
	v_cmp_gt_u32_e32 vcc, 64, v180
	s_nop 0
	v_writelane_b32 v252, s5, 1
	v_writelane_b32 v252, s6, 2
	v_writelane_b32 v252, s7, 3
	v_writelane_b32 v252, s8, 4
	v_writelane_b32 v252, s9, 5
	v_writelane_b32 v252, s10, 6
	v_writelane_b32 v252, s11, 7
	s_and_saveexec_b64 s[4:5], vcc
	v_lshl_add_u32 v1, v180, 2, 0
	v_add_u32_e32 v1, 0x20000, v1
	v_mov_b32_e32 v2, 0
	ds_write_b32 v1, v2
	s_or_b64 exec, exec, s[4:5]
	s_waitcnt lgkmcnt(0)
	s_barrier
	s_add_u32 s22, s66, 0x36230000
	s_getreg_b32 s3, hwreg(HW_REG_XCC_ID, 0, 4)
	s_addc_u32 s23, s67, 0
	s_and_b32 s3, s3, 15
	v_cmp_ne_u32_e64 s[4:5], 0, v180
	v_cmp_eq_u32_e64 s[8:9], 0, v180
	s_mov_b64 s[6:7], exec
	s_nop 0
	v_writelane_b32 v252, s8, 8
	s_nop 1
	v_writelane_b32 v252, s9, 9
	s_and_b64 s[8:9], s[6:7], s[8:9]
	s_mov_b64 exec, s[8:9]
	s_cbranch_execz .LBB0_5
	s_mov_b64 s[8:9], exec
	v_mbcnt_lo_u32_b32 v1, s8, 0
	v_mbcnt_hi_u32_b32 v1, s9, v1
	v_cmp_eq_u32_e32 vcc, 0, v1
	s_and_b64 s[10:11], exec, vcc
	s_mov_b64 exec, s[10:11]
	s_cbranch_execz .LBB0_5
	s_lshl_b32 s10, s3, 8
	s_bcnt1_i32_b64 s8, s[8:9]
	v_mov_b32_e32 v1, s10
	v_mov_b32_e32 v2, s8
	global_atomic_add v1, v2, s[22:23] offset:1024
